# SWA w_o E_RES epilogue de-serialized as well (bias flag handled with an always-valid pointer)
# baseline (speedup 1.0000x reference)
.LBB0_453:
	s_or_b64 exec, exec, s[4:5]
	v_readlane_b32 s8, v246, 42
	v_readlane_b32 s9, v246, 43
	s_mov_b64 s[4:5], 0
	s_mul_i32 s54, s3, 0x1800
	s_andn2_b64 vcc, exec, s[8:9]
	s_lshl_b32 s10, s3, 10
	s_waitcnt lgkmcnt(0)
	s_barrier
	s_cbranch_vccnz .LBB0_470
	s_add_u32 s11, s50, s4
	s_addc_u32 s58, s51, s5
	s_add_u32 s8, s11, 0x100000
	s_addc_u32 s9, s58, 0
	s_lshl_b64 s[4:5], s[54:55], 2
	s_add_u32 s4, s11, s4
	s_addc_u32 s5, s58, s5
	s_add_u32 s80, s4, 0x3000
	v_readlane_b32 s12, v246, 0
	s_addc_u32 s81, s5, 0
	s_lshl_b32 s4, s40, 10
	s_mov_b32 s5, s55
	v_readlane_b32 s20, v246, 8
	v_readlane_b32 s21, v246, 9
	v_readlane_b32 s22, v246, 10
	v_readlane_b32 s23, v246, 11
	v_readlane_b32 s24, v246, 12
	v_readlane_b32 s25, v246, 13
	s_lshl_b64 s[4:5], s[4:5], 2
	v_readlane_b32 s26, v246, 14
	v_readlane_b32 s27, v246, 15
	s_mov_b64 s[20:21], s[24:25]
	s_add_u32 s82, s20, s4
	s_addc_u32 s83, s21, s5
	s_add_u32 s84, s11, 0x80000
	s_addc_u32 s85, s58, 0
	s_add_i32 s4, s10, 0xfffffc00
	s_mov_b32 s5, s55
	s_lshl_b64 s[4:5], s[4:5], 2
	v_readlane_b32 s13, v246, 1
	v_readlane_b32 s14, v246, 2
	v_readlane_b32 s15, v246, 3
	v_readlane_b32 s16, v246, 4
	v_readlane_b32 s17, v246, 5
	v_readlane_b32 s18, v246, 6
	v_readlane_b32 s19, v246, 7
	s_mov_b64 s[22:23], s[26:27]
	s_add_u32 s86, s66, s4
	s_addc_u32 s87, s67, s5
	v_readlane_b32 s12, v246, 21
	v_readlane_b32 s13, v246, 22
	s_add_u32 s88, s12, s4
	s_addc_u32 s89, s13, s5
	s_add_u32 s4, s11, s6
	s_addc_u32 s5, s58, s7
	s_add_u32 s11, s11, 0x15100000
	s_addc_u32 s58, s58, 0
	s_add_u32 s59, s4, 0xb140000
	s_addc_u32 s60, s5, 0
	s_mov_b32 s61, s2
	v_readlane_b32 s14, v246, 23
	v_readlane_b32 s15, v246, 24
	v_readlane_b32 s16, v246, 25
	v_readlane_b32 s17, v246, 26
	v_readlane_b32 s18, v246, 27
	v_readlane_b32 s19, v246, 28
	v_readlane_b32 s20, v246, 29
	v_readlane_b32 s21, v246, 30
	v_readlane_b32 s22, v246, 31
	v_readlane_b32 s23, v246, 32
	v_readlane_b32 s24, v246, 33
	v_readlane_b32 s25, v246, 34
	v_readlane_b32 s26, v246, 35
	v_readlane_b32 s27, v246, 36
	s_branch .LBB0_456
.LBB0_456:
	s_lshl_b32 s4, s61, 5
	s_and_b32 s4, s4, 0xe0
	s_ashr_i32 s5, s61, 3
	s_add_i32 s4, s4, s5
	s_ashr_i32 s5, s4, 31
	s_lshr_b32 s5, s5, 27
	s_add_i32 s5, s4, s5
	s_and_b32 s6, s5, 0xffe0
	s_sub_i32 s4, s4, s6
	s_bfe_i32 s6, s4, 0x80000
	s_bfe_u32 s6, s6, 0x3000c
	s_add_i32 s6, s4, s6
	s_bfe_i32 s7, s6, 0x80000
	s_and_b32 s6, s6, 0xf8
	s_sub_i32 s4, s4, s6
	s_sext_i32_i8 s4, s4
	s_lshl_b32 s5, s5, 6
	s_sext_i32_i16 s7, s7
	s_and_b32 s5, s5, 0xfffff800
	s_lshl_b32 s4, s4, 8
	s_add_i32 s4, s4, s5
	s_lshl_b32 s5, s7, 5
	s_and_b32 s6, s5, 0xffffff00
	v_mov_b32_e32 v2, v162
	s_ashr_i32 s5, s4, 31
	s_lshl_b64 s[72:73], s[4:5], 11
	v_ashrrev_i32_e32 v3, 6, v2
	v_lshlrev_b32_e32 v0, 4, v2
	v_and_b32_e32 v4, 32, v2
	v_ashrrev_i32_e32 v6, 3, v2
	v_bfe_u32 v7, v2, 2, 4
	v_and_or_b32 v5, v6, s46, v7
	v_lshlrev_b32_e32 v8, 5, v3
	v_bitop3_b32 v0, v0, v4, 48 bitop3:0x6c
	s_add_u32 s90, s11, s72
	v_and_b32_e32 v8, 32, v8
	v_lshrrev_b32_e32 v9, 1, v0
	s_addc_u32 s91, s58, s73
	s_ashr_i32 s7, s6, 31
	v_lshlrev_b32_e32 v0, 10, v5
	s_lshl_b64 s[72:73], s[6:7], 11
	v_or3_b32 v0, v8, v9, v0
	s_waitcnt vmcnt(20)
	v_lshl_add_u32 v131, v3, 10, v179
	s_waitcnt vmcnt(17)
	v_ashrrev_i32_e32 v144, 8, v2
	v_and_b32_e32 v145, 15, v2
	v_and_b32_e32 v130, 63, v2
	s_waitcnt vmcnt(16)
	v_and_b32_e32 v146, 3, v3
	s_add_u32 s92, s59, s72
	v_and_b32_e32 v10, 48, v2
	v_lshlrev_b32_e32 v4, 2, v2
	v_readfirstlane_b32 s5, v2
	v_add_u32_e32 v12, 0x8000, v131
	v_lshlrev_b64 v[2:3], 1, v[0:1]
	v_readfirstlane_b32 s7, v131
	s_addc_u32 s93, s60, s73
	v_and_b32_e32 v11, 32, v4
	v_lshl_add_u64 v[4:5], s[90:91], 0, v[2:3]
	s_mov_b32 m0, s7
	v_readfirstlane_b32 s7, v12
	global_load_lds_dwordx4 v[4:5], off
	v_lshl_add_u64 v[2:3], s[92:93], 0, v[2:3]
	s_mov_b32 m0, s7
	v_add_u32_e32 v12, 0x2000, v131
	global_load_lds_dwordx4 v[2:3], off
	v_add_u32_e32 v2, 0x10000, v0
	v_mov_b32_e32 v3, v1
	v_lshlrev_b64 v[2:3], 1, v[2:3]
	v_readfirstlane_b32 s7, v12
	v_lshl_add_u64 v[4:5], s[90:91], 0, v[2:3]
	s_mov_b32 m0, s7
	v_lshl_add_u64 v[2:3], s[92:93], 0, v[2:3]
	global_load_lds_dwordx4 v[4:5], off
	v_add_u32_e32 v4, 0xa000, v131
	v_add_u32_e32 v12, 0x4000, v131
	v_readfirstlane_b32 s7, v4
	s_mov_b32 m0, s7
	v_readfirstlane_b32 s7, v12
	global_load_lds_dwordx4 v[2:3], off
	v_add_u32_e32 v2, 0x20000, v0
	v_mov_b32_e32 v3, v1
	v_lshlrev_b64 v[2:3], 1, v[2:3]
	v_lshl_add_u64 v[4:5], s[90:91], 0, v[2:3]
	s_mov_b32 m0, s7
	v_lshl_add_u64 v[2:3], s[92:93], 0, v[2:3]
	global_load_lds_dwordx4 v[4:5], off
	v_add_u32_e32 v4, 0xc000, v131
	v_add_u32_e32 v0, 0x30000, v0
	v_readfirstlane_b32 s7, v4
	s_mov_b32 m0, s7
	s_cmpk_gt_u32 s5, 0xff
	global_load_lds_dwordx4 v[2:3], off
	v_lshlrev_b64 v[2:3], 1, v[0:1]
	v_add_u32_e32 v0, 0x6000, v131
	v_lshl_add_u64 v[4:5], s[90:91], 0, v[2:3]
	v_readfirstlane_b32 s7, v0
	v_add_u32_e32 v0, 0xe000, v131
	s_mov_b32 m0, s7
	v_readfirstlane_b32 s7, v0
	global_load_lds_dwordx4 v[4:5], off
	v_lshl_add_u64 v[2:3], s[92:93], 0, v[2:3]
	s_mov_b32 m0, s7
	v_lshlrev_b32_e32 v0, 6, v145
	global_load_lds_dwordx4 v[2:3], off
	s_cselect_b64 s[94:95], -1, 0
	s_cmpk_lt_u32 s5, 0x100
	v_bitop3_b32 v132, v11, v0, v10 bitop3:0xde
	s_cselect_b64 s[96:97], -1, 0
	v_lshlrev_b32_e32 v0, 10, v6
	s_waitcnt vmcnt(0)
	v_and_or_b32 v0, v0, s38, v9
	v_lshlrev_b32_e32 v2, 10, v7
	v_or3_b32 v135, v0, v2, v8
	v_mov_b32_e32 v2, 0
	v_lshlrev_b32_e32 v133, 14, v144
	v_lshlrev_b32_e32 v134, 13, v146
	s_mov_b32 s5, 0
	s_mov_b32 s7, 0
	v_mov_b32_e32 v3, v2
	v_mov_b32_e32 v4, v2
	v_mov_b32_e32 v5, v2
	v_mov_b32_e32 v6, v2
	v_mov_b32_e32 v7, v2
	v_mov_b32_e32 v8, v2
	v_mov_b32_e32 v9, v2
	v_mov_b32_e32 v10, v2
	v_mov_b32_e32 v11, v2
	v_mov_b32_e32 v12, v2
	v_mov_b32_e32 v13, v2
	v_mov_b32_e32 v14, v2
	v_mov_b32_e32 v15, v2
	v_mov_b32_e32 v16, v2
	v_mov_b32_e32 v17, v2
	v_mov_b32_e32 v18, v2
	v_mov_b32_e32 v19, v2
	v_mov_b32_e32 v20, v2
	v_mov_b32_e32 v21, v2
	v_mov_b32_e32 v22, v2
	v_mov_b32_e32 v23, v2
	v_mov_b32_e32 v24, v2
	v_mov_b32_e32 v25, v2
	v_mov_b32_e32 v26, v2
	v_mov_b32_e32 v27, v2
	v_mov_b32_e32 v28, v2
	v_mov_b32_e32 v29, v2
	v_mov_b32_e32 v30, v2
	v_mov_b32_e32 v31, v2
	v_mov_b32_e32 v32, v2
	v_mov_b32_e32 v33, v2
	v_mov_b32_e32 v34, v2
	v_mov_b32_e32 v35, v2
	v_mov_b32_e32 v36, v2
	v_mov_b32_e32 v37, v2
	v_mov_b32_e32 v38, v2
	v_mov_b32_e32 v39, v2
	v_mov_b32_e32 v40, v2
	v_mov_b32_e32 v41, v2
	v_mov_b32_e32 v42, v2
	v_mov_b32_e32 v43, v2
	v_mov_b32_e32 v44, v2
	v_mov_b32_e32 v45, v2
	v_mov_b32_e32 v46, v2
	v_mov_b32_e32 v47, v2
	v_mov_b32_e32 v48, v2
	v_mov_b32_e32 v49, v2
	v_mov_b32_e32 v50, v2
	v_mov_b32_e32 v51, v2
	v_mov_b32_e32 v52, v2
	v_mov_b32_e32 v53, v2
	v_mov_b32_e32 v54, v2
	v_mov_b32_e32 v55, v2
	v_mov_b32_e32 v56, v2
	v_mov_b32_e32 v57, v2
	v_mov_b32_e32 v58, v2
	v_mov_b32_e32 v59, v2
	v_mov_b32_e32 v60, v2
	v_mov_b32_e32 v61, v2
	s_waitcnt vmcnt(0)
	v_mov_b32_e32 v62, v2
	v_mov_b32_e32 v63, v2
	v_mov_b32_e32 v64, v2
	v_mov_b32_e32 v65, v2
	v_mov_b32_e32 v66, v2
	v_mov_b32_e32 v67, v2
	v_mov_b32_e32 v68, v2
	v_mov_b32_e32 v69, v2
	v_mov_b32_e32 v70, v2
	v_mov_b32_e32 v71, v2
	v_mov_b32_e32 v72, v2
	v_mov_b32_e32 v73, v2
	v_mov_b32_e32 v74, v2
	v_mov_b32_e32 v75, v2
	v_mov_b32_e32 v76, v2
	v_mov_b32_e32 v77, v2
	v_mov_b32_e32 v78, v2
	v_mov_b32_e32 v79, v2
	v_mov_b32_e32 v80, v2
	v_mov_b32_e32 v81, v2
	v_mov_b32_e32 v82, v2
	v_mov_b32_e32 v83, v2
	v_mov_b32_e32 v84, v2
	v_mov_b32_e32 v85, v2
	v_mov_b32_e32 v86, v2
	v_mov_b32_e32 v87, v2
	v_mov_b32_e32 v88, v2
	v_mov_b32_e32 v89, v2
	v_mov_b32_e32 v90, v2
	v_mov_b32_e32 v91, v2
	v_mov_b32_e32 v92, v2
	v_mov_b32_e32 v93, v2
	v_mov_b32_e32 v94, v2
	v_mov_b32_e32 v95, v2
	v_mov_b32_e32 v96, v2
	v_mov_b32_e32 v97, v2
	v_mov_b32_e32 v98, v2
	v_mov_b32_e32 v99, v2
	v_mov_b32_e32 v100, v2
	v_mov_b32_e32 v101, v2
	v_mov_b32_e32 v102, v2
	v_mov_b32_e32 v103, v2
	v_mov_b32_e32 v104, v2
	v_mov_b32_e32 v105, v2
	v_mov_b32_e32 v106, v2
	v_mov_b32_e32 v107, v2
	v_mov_b32_e32 v108, v2
	v_mov_b32_e32 v109, v2
	v_mov_b32_e32 v110, v2
	v_mov_b32_e32 v111, v2
	v_mov_b32_e32 v112, v2
	v_mov_b32_e32 v113, v2
	v_mov_b32_e32 v114, v2
	v_mov_b32_e32 v115, v2
	v_mov_b32_e32 v116, v2
	v_mov_b32_e32 v117, v2
	v_mov_b32_e32 v118, v2
	v_mov_b32_e32 v119, v2
	v_mov_b32_e32 v120, v2
	v_mov_b32_e32 v121, v2
	v_mov_b32_e32 v122, v2
	v_mov_b32_e32 v123, v2
	v_mov_b32_e32 v124, v2
	v_mov_b32_e32 v125, v2
	v_mov_b32_e32 v126, v2
	v_mov_b32_e32 v127, v2
	v_mov_b32_e32 v128, v2
	v_mov_b32_e32 v129, v2
	s_waitcnt lgkmcnt(0)
	s_barrier
	s_branch .LBB0_458

.LBB0_462:
	s_add_i32 s5, s36, 0x400
	v_add3_u32 v142, s39, v134, v132
	v_lshrrev_b32_e32 v0, 4, v130
	v_add3_u32 v147, s5, v133, v132
	s_setprio 3
	ds_read_b128 v[130:133], v142
	ds_read_b128 v[134:137], v142 offset:2048
	ds_read_b128 v[138:141], v142 offset:4096
	ds_read_b128 v[148:151], v142 offset:6144
	ds_read_b128 v[152:155], v147
	ds_read_b128 v[156:159], v147 offset:2048
	ds_read_b128 v[166:169], v147 offset:4096
	ds_read_b128 v[170:173], v147 offset:6144
	ds_read_b128 v[174:177], v147 offset:8192
	s_waitcnt lgkmcnt(4)
	v_mfma_f32_16x16x32_bf16 v[126:129], v[130:133], v[152:155], v[126:129]
	v_mfma_f32_16x16x32_bf16 v[122:125], v[134:137], v[152:155], v[122:125]
	v_mfma_f32_16x16x32_bf16 v[118:121], v[138:141], v[152:155], v[118:121]
	v_mfma_f32_16x16x32_bf16 v[114:117], v[148:151], v[152:155], v[114:117]
	ds_read_b128 v[152:155], v147 offset:10240
	s_waitcnt lgkmcnt(4)
	v_mfma_f32_16x16x32_bf16 v[110:113], v[130:133], v[156:159], v[110:113]
	v_mfma_f32_16x16x32_bf16 v[106:109], v[134:137], v[156:159], v[106:109]
	v_mfma_f32_16x16x32_bf16 v[186:189], v[138:141], v[156:159], v[102:105]
	v_mfma_f32_16x16x32_bf16 v[156:159], v[148:151], v[156:159], v[98:101]
	s_nop 2
	ds_read_b128 v[98:101], v147 offset:12288
	s_waitcnt lgkmcnt(4)
	v_mfma_f32_16x16x32_bf16 v[190:193], v[130:133], v[166:169], v[94:97]
	v_mfma_f32_16x16x32_bf16 v[90:93], v[134:137], v[166:169], v[90:93]
	v_mfma_f32_16x16x32_bf16 v[86:89], v[138:141], v[166:169], v[86:89]
	v_mfma_f32_16x16x32_bf16 v[82:85], v[148:151], v[166:169], v[82:85]
	ds_read_b128 v[94:97], v147 offset:14336
	s_waitcnt lgkmcnt(4)
	v_mfma_f32_16x16x32_bf16 v[78:81], v[130:133], v[170:173], v[78:81]
	v_mfma_f32_16x16x32_bf16 v[74:77], v[134:137], v[170:173], v[74:77]
	v_mfma_f32_16x16x32_bf16 v[70:73], v[138:141], v[170:173], v[70:73]
	v_mfma_f32_16x16x32_bf16 v[166:169], v[148:151], v[170:173], v[66:69]
	s_waitcnt lgkmcnt(3)
	v_mfma_f32_16x16x32_bf16 v[170:173], v[130:133], v[174:177], v[62:65]
	v_mfma_f32_16x16x32_bf16 v[194:197], v[134:137], v[174:177], v[58:61]
	v_mfma_f32_16x16x32_bf16 v[198:201], v[138:141], v[174:177], v[54:57]
	v_mfma_f32_16x16x32_bf16 v[174:177], v[148:151], v[174:177], v[50:53]
	s_waitcnt lgkmcnt(2)
	v_mfma_f32_16x16x32_bf16 v[202:205], v[130:133], v[152:155], v[46:49]
	v_mfma_f32_16x16x32_bf16 v[42:45], v[134:137], v[152:155], v[42:45]
	v_mfma_f32_16x16x32_bf16 v[38:41], v[138:141], v[152:155], v[38:41]
	v_mfma_f32_16x16x32_bf16 v[34:37], v[148:151], v[152:155], v[34:37]
	s_waitcnt lgkmcnt(1)
	v_mfma_f32_16x16x32_bf16 v[30:33], v[130:133], v[98:101], v[30:33]
	v_mfma_f32_16x16x32_bf16 v[152:155], v[134:137], v[98:101], v[26:29]
	v_mfma_f32_16x16x32_bf16 v[206:209], v[138:141], v[98:101], v[22:25]
	v_mfma_f32_16x16x32_bf16 v[210:213], v[148:151], v[98:101], v[18:21]
	s_waitcnt lgkmcnt(0)
	v_mfma_f32_16x16x32_bf16 v[148:151], v[148:151], v[94:97], v[2:5]
	v_mfma_f32_16x16x32_bf16 v[214:217], v[130:133], v[94:97], v[14:17]
	v_mfma_f32_16x16x32_bf16 v[218:221], v[134:137], v[94:97], v[10:13]
	v_mfma_f32_16x16x32_bf16 v[222:225], v[138:141], v[94:97], v[6:9]
	s_setprio 0
	s_setprio 3
	ds_read_b128 v[226:229], v142 offset:1024
	ds_read_b128 v[230:233], v142 offset:3072
	ds_read_b128 v[234:237], v142 offset:5120
	ds_read_b128 v[238:241], v142 offset:7168
	ds_read_b128 v[2:5], v147 offset:1024
	ds_read_b128 v[6:9], v147 offset:3072
	ds_read_b128 v[10:13], v147 offset:5120
	ds_read_b128 v[14:17], v147 offset:7168
	ds_read_b128 v[242:245], v147 offset:9216
	s_waitcnt lgkmcnt(4)
	v_mfma_f32_16x16x32_bf16 v[140:143], v[226:229], v[2:5], v[126:129]
	v_mfma_f32_16x16x32_bf16 v[100:103], v[230:233], v[2:5], v[122:125]
	v_mfma_f32_16x16x32_bf16 v[64:67], v[234:237], v[2:5], v[118:121]
	v_mfma_f32_16x16x32_bf16 v[26:29], v[238:241], v[2:5], v[114:117]
	ds_read_b128 v[2:5], v147 offset:11264
	s_waitcnt lgkmcnt(4)
	v_mfma_f32_16x16x32_bf16 v[136:139], v[226:229], v[6:9], v[110:113]
	v_mfma_f32_16x16x32_bf16 v[96:99], v[230:233], v[6:9], v[106:109]
	v_mfma_f32_16x16x32_bf16 v[58:61], v[234:237], v[6:9], v[186:189]
	v_mfma_f32_16x16x32_bf16 v[22:25], v[238:241], v[6:9], v[156:159]
	s_nop 0
	ds_read_b128 v[104:107], v147 offset:13312
	s_waitcnt lgkmcnt(4)
	v_mfma_f32_16x16x32_bf16 v[132:135], v[226:229], v[10:13], v[190:193]
	v_mfma_f32_16x16x32_bf16 v[92:95], v[230:233], v[10:13], v[90:93]
	v_mfma_f32_16x16x32_bf16 v[54:57], v[234:237], v[10:13], v[86:89]
	v_mfma_f32_16x16x32_bf16 v[18:21], v[238:241], v[10:13], v[82:85]
	ds_read_b128 v[108:111], v147 offset:15360
	s_waitcnt lgkmcnt(4)
	v_mfma_f32_16x16x32_bf16 v[128:131], v[226:229], v[14:17], v[78:81]
	v_mfma_f32_16x16x32_bf16 v[88:91], v[230:233], v[14:17], v[74:77]
	v_mfma_f32_16x16x32_bf16 v[50:53], v[234:237], v[14:17], v[70:73]
	v_mfma_f32_16x16x32_bf16 v[14:17], v[238:241], v[14:17], v[166:169]
	s_waitcnt lgkmcnt(3)
	v_mfma_f32_16x16x32_bf16 v[124:127], v[226:229], v[242:245], v[170:173]
	v_mfma_f32_16x16x32_bf16 v[84:87], v[230:233], v[242:245], v[194:197]
	v_mfma_f32_16x16x32_bf16 v[46:49], v[234:237], v[242:245], v[198:201]
	v_mfma_f32_16x16x32_bf16 v[10:13], v[238:241], v[242:245], v[174:177]
	s_waitcnt lgkmcnt(2)
	v_mfma_f32_16x16x32_bf16 v[120:123], v[226:229], v[2:5], v[202:205]
	v_mfma_f32_16x16x32_bf16 v[80:83], v[230:233], v[2:5], v[42:45]
	v_mfma_f32_16x16x32_bf16 v[42:45], v[234:237], v[2:5], v[38:41]
	v_mfma_f32_16x16x32_bf16 v[6:9], v[238:241], v[2:5], v[34:37]
	s_waitcnt lgkmcnt(1)
	v_mfma_f32_16x16x32_bf16 v[112:115], v[226:229], v[104:107], v[30:33]
	v_mfma_f32_16x16x32_bf16 v[72:75], v[230:233], v[104:107], v[152:155]
	v_mfma_f32_16x16x32_bf16 v[38:41], v[234:237], v[104:107], v[206:209]
	v_mfma_f32_16x16x32_bf16 v[2:5], v[238:241], v[104:107], v[210:213]
	s_waitcnt lgkmcnt(0)
	v_mfma_f32_16x16x32_bf16 v[104:107], v[226:229], v[108:111], v[214:217]
	v_mfma_f32_16x16x32_bf16 v[68:71], v[230:233], v[108:111], v[218:221]
	v_mfma_f32_16x16x32_bf16 v[34:37], v[234:237], v[108:111], v[222:225]
	v_mfma_f32_16x16x32_bf16 v[30:33], v[238:241], v[108:111], v[148:151]
	s_setprio 0
	v_lshl_or_b32 v62, v146, 6, s6
	s_waitcnt vmcnt(0)
	s_barrier
	v_lshl_add_u32 v150, v0, 2, v62
	v_lshlrev_b32_e32 v0, 7, v144
	v_add3_u32 v62, v0, s4, v145
	v_lshlrev_b32_e32 v63, 12, v62
	v_lshl_add_u32 v63, v150, 2, v63
	v_add_u32_e32 v151, 0x10000, v63
	v_add_u32_e32 v226, 0x20000, v63
	v_add_u32_e32 v227, 0x30000, v63
	v_add_u32_e32 v228, 0x40000, v63
	v_add_u32_e32 v229, 0x50000, v63
	v_add_u32_e32 v230, 0x60000, v63
	v_add_u32_e32 v231, 0x70000, v63
	v_lshlrev_b32_e32 v232, 2, v150
	v_lshlrev_b32_e32 v233, 3, v62
	global_load_dwordx2 v[148:149], v233, s[84:85]
	global_load_dwordx2 v[160:161], v233, s[84:85] offset:128
	global_load_dwordx2 v[174:175], v233, s[84:85] offset:256
	global_load_dwordx2 v[176:177], v233, s[84:85] offset:384
	global_load_dwordx2 v[186:187], v233, s[84:85] offset:512
	global_load_dwordx2 v[188:189], v233, s[84:85] offset:640
	global_load_dwordx2 v[190:191], v233, s[84:85] offset:768
	global_load_dwordx2 v[192:193], v233, s[84:85] offset:896
	s_and_b64 vcc, exec, s[34:35]
	s_cselect_b64 s[14:15], s[82:83], s[80:81]
	global_load_dwordx4 v[194:197], v232, s[80:81]
	global_load_dwordx4 v[198:201], v232, s[86:87]
	global_load_dwordx4 v[202:205], v232, s[88:89]
	global_load_dwordx4 v[206:209], v232, s[14:15]
	global_load_dwordx4 v[76:79], v63, s[8:9]
	global_load_dwordx4 v[108:111], v151, s[8:9]
	global_load_dwordx4 v[116:119], v226, s[8:9]
	global_load_dwordx4 v[144:147], v227, s[8:9]
	global_load_dwordx4 v[152:155], v228, s[8:9]
	global_load_dwordx4 v[156:159], v229, s[8:9]
	global_load_dwordx4 v[166:169], v230, s[8:9]
	global_load_dwordx4 v[170:173], v231, s[8:9]
	global_load_dwordx4 v[210:213], v232, s[80:81] offset:64
	global_load_dwordx4 v[214:217], v232, s[86:87] offset:64
	global_load_dwordx4 v[218:221], v232, s[88:89] offset:64
	global_load_dwordx4 v[222:225], v232, s[14:15] offset:64
	s_waitcnt vmcnt(12)
	s_and_b64 vcc, exec, s[34:35]
	s_cbranch_vccnz .Ler_swa_hb0
	v_mov_b32_e32 v206, 0
	v_mov_b32_e32 v207, 0
	v_mov_b32_e32 v208, 0
	v_mov_b32_e32 v209, 0
.Ler_swa_hb0:
	v_pk_mul_f32 v[198:199], v[198:199], s[70:71] op_sel_hi:[1,0]
	v_pk_mul_f32 v[200:201], v[200:201], s[70:71] op_sel_hi:[1,0]
	v_pk_mul_f32 v[202:203], v[202:203], s[70:71] op_sel_hi:[1,0]
	v_pk_mul_f32 v[204:205], v[204:205], s[70:71] op_sel_hi:[1,0]
	s_waitcnt vmcnt(11)
	v_pk_add_f32 v[140:141], v[140:141], v[206:207]
	v_pk_add_f32 v[142:143], v[142:143], v[208:209]
	v_pk_add_f32 v[76:77], v[76:77], v[148:149] op_sel_hi:[1,0] neg_lo:[0,1] neg_hi:[0,1]
	v_pk_add_f32 v[78:79], v[78:79], v[148:149] op_sel_hi:[1,0] neg_lo:[0,1] neg_hi:[0,1]
	v_pk_mul_f32 v[76:77], v[76:77], v[148:149] op_sel:[0,1]
	v_pk_mul_f32 v[78:79], v[78:79], v[148:149] op_sel:[0,1]
	v_pk_fma_f32 v[76:77], v[198:199], v[76:77], v[202:203]
	v_pk_fma_f32 v[78:79], v[200:201], v[78:79], v[204:205]
	v_pk_fma_f32 v[76:77], v[140:141], v[194:195], v[76:77]
	v_pk_fma_f32 v[78:79], v[142:143], v[196:197], v[78:79]
	global_store_dwordx4 v63, v[76:79], s[8:9]
	s_nop 1
	global_load_dwordx4 v[76:79], v63, s[8:9] offset:64
	s_waitcnt vmcnt(12)
	v_pk_add_f32 v[136:137], v[136:137], v[206:207]
	v_pk_add_f32 v[138:139], v[138:139], v[208:209]
	v_pk_add_f32 v[108:109], v[108:109], v[160:161] op_sel_hi:[1,0] neg_lo:[0,1] neg_hi:[0,1]
	v_pk_add_f32 v[110:111], v[110:111], v[160:161] op_sel_hi:[1,0] neg_lo:[0,1] neg_hi:[0,1]
	v_pk_mul_f32 v[108:109], v[108:109], v[160:161] op_sel:[0,1]
	v_pk_mul_f32 v[110:111], v[110:111], v[160:161] op_sel:[0,1]
	v_pk_fma_f32 v[108:109], v[198:199], v[108:109], v[202:203]
	v_pk_fma_f32 v[110:111], v[200:201], v[110:111], v[204:205]
	v_pk_fma_f32 v[108:109], v[136:137], v[194:195], v[108:109]
	v_pk_fma_f32 v[110:111], v[138:139], v[196:197], v[110:111]
	global_store_dwordx4 v151, v[108:111], s[8:9]
	s_nop 1
	global_load_dwordx4 v[108:111], v151, s[8:9] offset:64
	s_waitcnt vmcnt(13)
	v_pk_add_f32 v[132:133], v[132:133], v[206:207]
	v_pk_add_f32 v[134:135], v[134:135], v[208:209]
	v_pk_add_f32 v[116:117], v[116:117], v[174:175] op_sel_hi:[1,0] neg_lo:[0,1] neg_hi:[0,1]
	v_pk_add_f32 v[118:119], v[118:119], v[174:175] op_sel_hi:[1,0] neg_lo:[0,1] neg_hi:[0,1]
	v_pk_mul_f32 v[116:117], v[116:117], v[174:175] op_sel:[0,1]
	v_pk_mul_f32 v[118:119], v[118:119], v[174:175] op_sel:[0,1]
	v_pk_fma_f32 v[116:117], v[198:199], v[116:117], v[202:203]
	v_pk_fma_f32 v[118:119], v[200:201], v[118:119], v[204:205]
	v_pk_fma_f32 v[116:117], v[132:133], v[194:195], v[116:117]
	v_pk_fma_f32 v[118:119], v[134:135], v[196:197], v[118:119]
	global_store_dwordx4 v226, v[116:119], s[8:9]
	s_nop 1
	global_load_dwordx4 v[116:119], v226, s[8:9] offset:64
	s_waitcnt vmcnt(14)
	v_pk_add_f32 v[128:129], v[128:129], v[206:207]
	v_pk_add_f32 v[130:131], v[130:131], v[208:209]
	v_pk_add_f32 v[144:145], v[144:145], v[176:177] op_sel_hi:[1,0] neg_lo:[0,1] neg_hi:[0,1]
	v_pk_add_f32 v[146:147], v[146:147], v[176:177] op_sel_hi:[1,0] neg_lo:[0,1] neg_hi:[0,1]
	v_pk_mul_f32 v[144:145], v[144:145], v[176:177] op_sel:[0,1]
	v_pk_mul_f32 v[146:147], v[146:147], v[176:177] op_sel:[0,1]
	v_pk_fma_f32 v[144:145], v[198:199], v[144:145], v[202:203]
	v_pk_fma_f32 v[146:147], v[200:201], v[146:147], v[204:205]
	v_pk_fma_f32 v[144:145], v[128:129], v[194:195], v[144:145]
	v_pk_fma_f32 v[146:147], v[130:131], v[196:197], v[146:147]
	global_store_dwordx4 v227, v[144:147], s[8:9]
	s_nop 1
	global_load_dwordx4 v[144:147], v227, s[8:9] offset:64
	s_waitcnt vmcnt(15)
	v_pk_add_f32 v[124:125], v[124:125], v[206:207]
	v_pk_add_f32 v[126:127], v[126:127], v[208:209]
	v_pk_add_f32 v[152:153], v[152:153], v[186:187] op_sel_hi:[1,0] neg_lo:[0,1] neg_hi:[0,1]
	v_pk_add_f32 v[154:155], v[154:155], v[186:187] op_sel_hi:[1,0] neg_lo:[0,1] neg_hi:[0,1]
	v_pk_mul_f32 v[152:153], v[152:153], v[186:187] op_sel:[0,1]
	v_pk_mul_f32 v[154:155], v[154:155], v[186:187] op_sel:[0,1]
	v_pk_fma_f32 v[152:153], v[198:199], v[152:153], v[202:203]
	v_pk_fma_f32 v[154:155], v[200:201], v[154:155], v[204:205]
	v_pk_fma_f32 v[152:153], v[124:125], v[194:195], v[152:153]
	v_pk_fma_f32 v[154:155], v[126:127], v[196:197], v[154:155]
	global_store_dwordx4 v228, v[152:155], s[8:9]
	s_nop 1
	global_load_dwordx4 v[152:155], v228, s[8:9] offset:64
	s_waitcnt vmcnt(16)
	v_pk_add_f32 v[120:121], v[120:121], v[206:207]
	v_pk_add_f32 v[122:123], v[122:123], v[208:209]
	v_pk_add_f32 v[156:157], v[156:157], v[188:189] op_sel_hi:[1,0] neg_lo:[0,1] neg_hi:[0,1]
	v_pk_add_f32 v[158:159], v[158:159], v[188:189] op_sel_hi:[1,0] neg_lo:[0,1] neg_hi:[0,1]
	v_pk_mul_f32 v[156:157], v[156:157], v[188:189] op_sel:[0,1]
	v_pk_mul_f32 v[158:159], v[158:159], v[188:189] op_sel:[0,1]
	v_pk_fma_f32 v[156:157], v[198:199], v[156:157], v[202:203]
	v_pk_fma_f32 v[158:159], v[200:201], v[158:159], v[204:205]
	v_pk_fma_f32 v[156:157], v[120:121], v[194:195], v[156:157]
	v_pk_fma_f32 v[158:159], v[122:123], v[196:197], v[158:159]
	global_store_dwordx4 v229, v[156:159], s[8:9]
	s_nop 1
	global_load_dwordx4 v[156:159], v229, s[8:9] offset:64
	s_waitcnt vmcnt(17)
	v_pk_add_f32 v[112:113], v[112:113], v[206:207]
	v_pk_add_f32 v[114:115], v[114:115], v[208:209]
	v_pk_add_f32 v[166:167], v[166:167], v[190:191] op_sel_hi:[1,0] neg_lo:[0,1] neg_hi:[0,1]
	v_pk_add_f32 v[168:169], v[168:169], v[190:191] op_sel_hi:[1,0] neg_lo:[0,1] neg_hi:[0,1]
	v_pk_mul_f32 v[166:167], v[166:167], v[190:191] op_sel:[0,1]
	v_pk_mul_f32 v[168:169], v[168:169], v[190:191] op_sel:[0,1]
	v_pk_fma_f32 v[166:167], v[198:199], v[166:167], v[202:203]
	v_pk_fma_f32 v[168:169], v[200:201], v[168:169], v[204:205]
	v_pk_fma_f32 v[166:167], v[112:113], v[194:195], v[166:167]
	v_pk_fma_f32 v[168:169], v[114:115], v[196:197], v[168:169]
	global_store_dwordx4 v230, v[166:169], s[8:9]
	s_nop 1
	global_load_dwordx4 v[166:169], v230, s[8:9] offset:64
	s_waitcnt vmcnt(18)
	v_pk_add_f32 v[104:105], v[104:105], v[206:207]
	v_pk_add_f32 v[106:107], v[106:107], v[208:209]
	v_pk_add_f32 v[170:171], v[170:171], v[192:193] op_sel_hi:[1,0] neg_lo:[0,1] neg_hi:[0,1]
	v_pk_add_f32 v[172:173], v[172:173], v[192:193] op_sel_hi:[1,0] neg_lo:[0,1] neg_hi:[0,1]
	v_pk_mul_f32 v[170:171], v[170:171], v[192:193] op_sel:[0,1]
	v_pk_mul_f32 v[172:173], v[172:173], v[192:193] op_sel:[0,1]
	v_pk_fma_f32 v[170:171], v[198:199], v[170:171], v[202:203]
	v_pk_fma_f32 v[172:173], v[200:201], v[172:173], v[204:205]
	v_pk_fma_f32 v[170:171], v[104:105], v[194:195], v[170:171]
	v_pk_fma_f32 v[172:173], v[106:107], v[196:197], v[172:173]
	global_store_dwordx4 v231, v[170:173], s[8:9]
	s_nop 1
	global_load_dwordx4 v[170:173], v231, s[8:9] offset:64
	global_load_dwordx4 v[194:197], v232, s[80:81] offset:128
	global_load_dwordx4 v[198:201], v232, s[86:87] offset:128
	global_load_dwordx4 v[202:205], v232, s[88:89] offset:128
	global_load_dwordx4 v[206:209], v232, s[14:15] offset:128
	s_waitcnt vmcnt(20)
	s_and_b64 vcc, exec, s[34:35]
	s_cbranch_vccnz .Ler_swa_hb1
	v_mov_b32_e32 v222, 0
	v_mov_b32_e32 v223, 0
	v_mov_b32_e32 v224, 0
	v_mov_b32_e32 v225, 0
.Ler_swa_hb1:
	v_pk_mul_f32 v[214:215], v[214:215], s[70:71] op_sel_hi:[1,0]
	v_pk_mul_f32 v[216:217], v[216:217], s[70:71] op_sel_hi:[1,0]
	v_pk_mul_f32 v[218:219], v[218:219], s[70:71] op_sel_hi:[1,0]
	v_pk_mul_f32 v[220:221], v[220:221], s[70:71] op_sel_hi:[1,0]
	s_waitcnt vmcnt(18)
	v_pk_add_f32 v[100:101], v[100:101], v[222:223]
	v_pk_add_f32 v[102:103], v[102:103], v[224:225]
	v_pk_add_f32 v[76:77], v[76:77], v[148:149] op_sel_hi:[1,0] neg_lo:[0,1] neg_hi:[0,1]
	v_pk_add_f32 v[78:79], v[78:79], v[148:149] op_sel_hi:[1,0] neg_lo:[0,1] neg_hi:[0,1]
	v_pk_mul_f32 v[76:77], v[76:77], v[148:149] op_sel:[0,1]
	v_pk_mul_f32 v[78:79], v[78:79], v[148:149] op_sel:[0,1]
	v_pk_fma_f32 v[76:77], v[214:215], v[76:77], v[218:219]
	v_pk_fma_f32 v[78:79], v[216:217], v[78:79], v[220:221]
	v_pk_fma_f32 v[76:77], v[100:101], v[210:211], v[76:77]
	v_pk_fma_f32 v[78:79], v[102:103], v[212:213], v[78:79]
	global_store_dwordx4 v63, v[76:79], s[8:9] offset:64
	s_nop 1
	global_load_dwordx4 v[76:79], v63, s[8:9] offset:128
	s_waitcnt vmcnt(18)
	v_pk_add_f32 v[96:97], v[96:97], v[222:223]
	v_pk_add_f32 v[98:99], v[98:99], v[224:225]
	v_pk_add_f32 v[108:109], v[108:109], v[160:161] op_sel_hi:[1,0] neg_lo:[0,1] neg_hi:[0,1]
	v_pk_add_f32 v[110:111], v[110:111], v[160:161] op_sel_hi:[1,0] neg_lo:[0,1] neg_hi:[0,1]
	v_pk_mul_f32 v[108:109], v[108:109], v[160:161] op_sel:[0,1]
	v_pk_mul_f32 v[110:111], v[110:111], v[160:161] op_sel:[0,1]
	v_pk_fma_f32 v[108:109], v[214:215], v[108:109], v[218:219]
	v_pk_fma_f32 v[110:111], v[216:217], v[110:111], v[220:221]
	v_pk_fma_f32 v[108:109], v[96:97], v[210:211], v[108:109]
	v_pk_fma_f32 v[110:111], v[98:99], v[212:213], v[110:111]
	global_store_dwordx4 v151, v[108:111], s[8:9] offset:64
	s_nop 1
	global_load_dwordx4 v[108:111], v151, s[8:9] offset:128
	s_waitcnt vmcnt(18)
	v_pk_add_f32 v[92:93], v[92:93], v[222:223]
	v_pk_add_f32 v[94:95], v[94:95], v[224:225]
	v_pk_add_f32 v[116:117], v[116:117], v[174:175] op_sel_hi:[1,0] neg_lo:[0,1] neg_hi:[0,1]
	v_pk_add_f32 v[118:119], v[118:119], v[174:175] op_sel_hi:[1,0] neg_lo:[0,1] neg_hi:[0,1]
	v_pk_mul_f32 v[116:117], v[116:117], v[174:175] op_sel:[0,1]
	v_pk_mul_f32 v[118:119], v[118:119], v[174:175] op_sel:[0,1]
	v_pk_fma_f32 v[116:117], v[214:215], v[116:117], v[218:219]
	v_pk_fma_f32 v[118:119], v[216:217], v[118:119], v[220:221]
	v_pk_fma_f32 v[116:117], v[92:93], v[210:211], v[116:117]
	v_pk_fma_f32 v[118:119], v[94:95], v[212:213], v[118:119]
	global_store_dwordx4 v226, v[116:119], s[8:9] offset:64
	s_nop 1
	global_load_dwordx4 v[116:119], v226, s[8:9] offset:128
	s_waitcnt vmcnt(18)
	v_pk_add_f32 v[88:89], v[88:89], v[222:223]
	v_pk_add_f32 v[90:91], v[90:91], v[224:225]
	v_pk_add_f32 v[144:145], v[144:145], v[176:177] op_sel_hi:[1,0] neg_lo:[0,1] neg_hi:[0,1]
	v_pk_add_f32 v[146:147], v[146:147], v[176:177] op_sel_hi:[1,0] neg_lo:[0,1] neg_hi:[0,1]
	v_pk_mul_f32 v[144:145], v[144:145], v[176:177] op_sel:[0,1]
	v_pk_mul_f32 v[146:147], v[146:147], v[176:177] op_sel:[0,1]
	v_pk_fma_f32 v[144:145], v[214:215], v[144:145], v[218:219]
	v_pk_fma_f32 v[146:147], v[216:217], v[146:147], v[220:221]
	v_pk_fma_f32 v[144:145], v[88:89], v[210:211], v[144:145]
	v_pk_fma_f32 v[146:147], v[90:91], v[212:213], v[146:147]
	global_store_dwordx4 v227, v[144:147], s[8:9] offset:64
	s_nop 1
	global_load_dwordx4 v[144:147], v227, s[8:9] offset:128
	s_waitcnt vmcnt(18)
	v_pk_add_f32 v[84:85], v[84:85], v[222:223]
	v_pk_add_f32 v[86:87], v[86:87], v[224:225]
	v_pk_add_f32 v[152:153], v[152:153], v[186:187] op_sel_hi:[1,0] neg_lo:[0,1] neg_hi:[0,1]
	v_pk_add_f32 v[154:155], v[154:155], v[186:187] op_sel_hi:[1,0] neg_lo:[0,1] neg_hi:[0,1]
	v_pk_mul_f32 v[152:153], v[152:153], v[186:187] op_sel:[0,1]
	v_pk_mul_f32 v[154:155], v[154:155], v[186:187] op_sel:[0,1]
	v_pk_fma_f32 v[152:153], v[214:215], v[152:153], v[218:219]
	v_pk_fma_f32 v[154:155], v[216:217], v[154:155], v[220:221]
	v_pk_fma_f32 v[152:153], v[84:85], v[210:211], v[152:153]
	v_pk_fma_f32 v[154:155], v[86:87], v[212:213], v[154:155]
	global_store_dwordx4 v228, v[152:155], s[8:9] offset:64
	s_nop 1
	global_load_dwordx4 v[152:155], v228, s[8:9] offset:128
	s_waitcnt vmcnt(18)
	v_pk_add_f32 v[80:81], v[80:81], v[222:223]
	v_pk_add_f32 v[82:83], v[82:83], v[224:225]
	v_pk_add_f32 v[156:157], v[156:157], v[188:189] op_sel_hi:[1,0] neg_lo:[0,1] neg_hi:[0,1]
	v_pk_add_f32 v[158:159], v[158:159], v[188:189] op_sel_hi:[1,0] neg_lo:[0,1] neg_hi:[0,1]
	v_pk_mul_f32 v[156:157], v[156:157], v[188:189] op_sel:[0,1]
	v_pk_mul_f32 v[158:159], v[158:159], v[188:189] op_sel:[0,1]
	v_pk_fma_f32 v[156:157], v[214:215], v[156:157], v[218:219]
	v_pk_fma_f32 v[158:159], v[216:217], v[158:159], v[220:221]
	v_pk_fma_f32 v[156:157], v[80:81], v[210:211], v[156:157]
	v_pk_fma_f32 v[158:159], v[82:83], v[212:213], v[158:159]
	global_store_dwordx4 v229, v[156:159], s[8:9] offset:64
	s_nop 1
	global_load_dwordx4 v[156:159], v229, s[8:9] offset:128
	s_waitcnt vmcnt(18)
	v_pk_add_f32 v[72:73], v[72:73], v[222:223]
	v_pk_add_f32 v[74:75], v[74:75], v[224:225]
	v_pk_add_f32 v[166:167], v[166:167], v[190:191] op_sel_hi:[1,0] neg_lo:[0,1] neg_hi:[0,1]
	v_pk_add_f32 v[168:169], v[168:169], v[190:191] op_sel_hi:[1,0] neg_lo:[0,1] neg_hi:[0,1]
	v_pk_mul_f32 v[166:167], v[166:167], v[190:191] op_sel:[0,1]
	v_pk_mul_f32 v[168:169], v[168:169], v[190:191] op_sel:[0,1]
	v_pk_fma_f32 v[166:167], v[214:215], v[166:167], v[218:219]
	v_pk_fma_f32 v[168:169], v[216:217], v[168:169], v[220:221]
	v_pk_fma_f32 v[166:167], v[72:73], v[210:211], v[166:167]
	v_pk_fma_f32 v[168:169], v[74:75], v[212:213], v[168:169]
	global_store_dwordx4 v230, v[166:169], s[8:9] offset:64
	s_nop 1
	global_load_dwordx4 v[166:169], v230, s[8:9] offset:128
	s_waitcnt vmcnt(18)
	v_pk_add_f32 v[68:69], v[68:69], v[222:223]
	v_pk_add_f32 v[70:71], v[70:71], v[224:225]
	v_pk_add_f32 v[170:171], v[170:171], v[192:193] op_sel_hi:[1,0] neg_lo:[0,1] neg_hi:[0,1]
	v_pk_add_f32 v[172:173], v[172:173], v[192:193] op_sel_hi:[1,0] neg_lo:[0,1] neg_hi:[0,1]
	v_pk_mul_f32 v[170:171], v[170:171], v[192:193] op_sel:[0,1]
	v_pk_mul_f32 v[172:173], v[172:173], v[192:193] op_sel:[0,1]
	v_pk_fma_f32 v[170:171], v[214:215], v[170:171], v[218:219]
	v_pk_fma_f32 v[172:173], v[216:217], v[172:173], v[220:221]
	v_pk_fma_f32 v[170:171], v[68:69], v[210:211], v[170:171]
	v_pk_fma_f32 v[172:173], v[70:71], v[212:213], v[172:173]
	global_store_dwordx4 v231, v[170:173], s[8:9] offset:64
	s_nop 1
	global_load_dwordx4 v[170:173], v231, s[8:9] offset:128
	global_load_dwordx4 v[210:213], v232, s[80:81] offset:192
	global_load_dwordx4 v[214:217], v232, s[86:87] offset:192
	global_load_dwordx4 v[218:221], v232, s[88:89] offset:192
	global_load_dwordx4 v[222:225], v232, s[14:15] offset:192
	s_waitcnt vmcnt(20)
	s_and_b64 vcc, exec, s[34:35]
	s_cbranch_vccnz .Ler_swa_hb2
	v_mov_b32_e32 v206, 0
	v_mov_b32_e32 v207, 0
	v_mov_b32_e32 v208, 0
	v_mov_b32_e32 v209, 0
.Ler_swa_hb2:
	v_pk_mul_f32 v[198:199], v[198:199], s[70:71] op_sel_hi:[1,0]
	v_pk_mul_f32 v[200:201], v[200:201], s[70:71] op_sel_hi:[1,0]
	v_pk_mul_f32 v[202:203], v[202:203], s[70:71] op_sel_hi:[1,0]
	v_pk_mul_f32 v[204:205], v[204:205], s[70:71] op_sel_hi:[1,0]
	s_waitcnt vmcnt(18)
	v_pk_add_f32 v[64:65], v[64:65], v[206:207]
	v_pk_add_f32 v[66:67], v[66:67], v[208:209]
	v_pk_add_f32 v[76:77], v[76:77], v[148:149] op_sel_hi:[1,0] neg_lo:[0,1] neg_hi:[0,1]
	v_pk_add_f32 v[78:79], v[78:79], v[148:149] op_sel_hi:[1,0] neg_lo:[0,1] neg_hi:[0,1]
	v_pk_mul_f32 v[76:77], v[76:77], v[148:149] op_sel:[0,1]
	v_pk_mul_f32 v[78:79], v[78:79], v[148:149] op_sel:[0,1]
	v_pk_fma_f32 v[76:77], v[198:199], v[76:77], v[202:203]
	v_pk_fma_f32 v[78:79], v[200:201], v[78:79], v[204:205]
	v_pk_fma_f32 v[76:77], v[64:65], v[194:195], v[76:77]
	v_pk_fma_f32 v[78:79], v[66:67], v[196:197], v[78:79]
	global_store_dwordx4 v63, v[76:79], s[8:9] offset:128
	s_nop 1
	global_load_dwordx4 v[76:79], v63, s[8:9] offset:192
	s_waitcnt vmcnt(18)
	v_pk_add_f32 v[58:59], v[58:59], v[206:207]
	v_pk_add_f32 v[60:61], v[60:61], v[208:209]
	v_pk_add_f32 v[108:109], v[108:109], v[160:161] op_sel_hi:[1,0] neg_lo:[0,1] neg_hi:[0,1]
	v_pk_add_f32 v[110:111], v[110:111], v[160:161] op_sel_hi:[1,0] neg_lo:[0,1] neg_hi:[0,1]
	v_pk_mul_f32 v[108:109], v[108:109], v[160:161] op_sel:[0,1]
	v_pk_mul_f32 v[110:111], v[110:111], v[160:161] op_sel:[0,1]
	v_pk_fma_f32 v[108:109], v[198:199], v[108:109], v[202:203]
	v_pk_fma_f32 v[110:111], v[200:201], v[110:111], v[204:205]
	v_pk_fma_f32 v[108:109], v[58:59], v[194:195], v[108:109]
	v_pk_fma_f32 v[110:111], v[60:61], v[196:197], v[110:111]
	global_store_dwordx4 v151, v[108:111], s[8:9] offset:128
	s_nop 1
	global_load_dwordx4 v[108:111], v151, s[8:9] offset:192
	s_waitcnt vmcnt(18)
	v_pk_add_f32 v[54:55], v[54:55], v[206:207]
	v_pk_add_f32 v[56:57], v[56:57], v[208:209]
	v_pk_add_f32 v[116:117], v[116:117], v[174:175] op_sel_hi:[1,0] neg_lo:[0,1] neg_hi:[0,1]
	v_pk_add_f32 v[118:119], v[118:119], v[174:175] op_sel_hi:[1,0] neg_lo:[0,1] neg_hi:[0,1]
	v_pk_mul_f32 v[116:117], v[116:117], v[174:175] op_sel:[0,1]
	v_pk_mul_f32 v[118:119], v[118:119], v[174:175] op_sel:[0,1]
	v_pk_fma_f32 v[116:117], v[198:199], v[116:117], v[202:203]
	v_pk_fma_f32 v[118:119], v[200:201], v[118:119], v[204:205]
	v_pk_fma_f32 v[116:117], v[54:55], v[194:195], v[116:117]
	v_pk_fma_f32 v[118:119], v[56:57], v[196:197], v[118:119]
	global_store_dwordx4 v226, v[116:119], s[8:9] offset:128
	s_nop 1
	global_load_dwordx4 v[116:119], v226, s[8:9] offset:192
	s_waitcnt vmcnt(18)
	v_pk_add_f32 v[50:51], v[50:51], v[206:207]
	v_pk_add_f32 v[52:53], v[52:53], v[208:209]
	v_pk_add_f32 v[144:145], v[144:145], v[176:177] op_sel_hi:[1,0] neg_lo:[0,1] neg_hi:[0,1]
	v_pk_add_f32 v[146:147], v[146:147], v[176:177] op_sel_hi:[1,0] neg_lo:[0,1] neg_hi:[0,1]
	v_pk_mul_f32 v[144:145], v[144:145], v[176:177] op_sel:[0,1]
	v_pk_mul_f32 v[146:147], v[146:147], v[176:177] op_sel:[0,1]
	v_pk_fma_f32 v[144:145], v[198:199], v[144:145], v[202:203]
	v_pk_fma_f32 v[146:147], v[200:201], v[146:147], v[204:205]
	v_pk_fma_f32 v[144:145], v[50:51], v[194:195], v[144:145]
	v_pk_fma_f32 v[146:147], v[52:53], v[196:197], v[146:147]
	global_store_dwordx4 v227, v[144:147], s[8:9] offset:128
	s_nop 1
	global_load_dwordx4 v[144:147], v227, s[8:9] offset:192
	s_waitcnt vmcnt(18)
	v_pk_add_f32 v[46:47], v[46:47], v[206:207]
	v_pk_add_f32 v[48:49], v[48:49], v[208:209]
	v_pk_add_f32 v[152:153], v[152:153], v[186:187] op_sel_hi:[1,0] neg_lo:[0,1] neg_hi:[0,1]
	v_pk_add_f32 v[154:155], v[154:155], v[186:187] op_sel_hi:[1,0] neg_lo:[0,1] neg_hi:[0,1]
	v_pk_mul_f32 v[152:153], v[152:153], v[186:187] op_sel:[0,1]
	v_pk_mul_f32 v[154:155], v[154:155], v[186:187] op_sel:[0,1]
	v_pk_fma_f32 v[152:153], v[198:199], v[152:153], v[202:203]
	v_pk_fma_f32 v[154:155], v[200:201], v[154:155], v[204:205]
	v_pk_fma_f32 v[152:153], v[46:47], v[194:195], v[152:153]
	v_pk_fma_f32 v[154:155], v[48:49], v[196:197], v[154:155]
	global_store_dwordx4 v228, v[152:155], s[8:9] offset:128
	s_nop 1
	global_load_dwordx4 v[152:155], v228, s[8:9] offset:192
	s_waitcnt vmcnt(18)
	v_pk_add_f32 v[42:43], v[42:43], v[206:207]
	v_pk_add_f32 v[44:45], v[44:45], v[208:209]
	v_pk_add_f32 v[156:157], v[156:157], v[188:189] op_sel_hi:[1,0] neg_lo:[0,1] neg_hi:[0,1]
	v_pk_add_f32 v[158:159], v[158:159], v[188:189] op_sel_hi:[1,0] neg_lo:[0,1] neg_hi:[0,1]
	v_pk_mul_f32 v[156:157], v[156:157], v[188:189] op_sel:[0,1]
	v_pk_mul_f32 v[158:159], v[158:159], v[188:189] op_sel:[0,1]
	v_pk_fma_f32 v[156:157], v[198:199], v[156:157], v[202:203]
	v_pk_fma_f32 v[158:159], v[200:201], v[158:159], v[204:205]
	v_pk_fma_f32 v[156:157], v[42:43], v[194:195], v[156:157]
	v_pk_fma_f32 v[158:159], v[44:45], v[196:197], v[158:159]
	global_store_dwordx4 v229, v[156:159], s[8:9] offset:128
	s_nop 1
	global_load_dwordx4 v[156:159], v229, s[8:9] offset:192
	s_waitcnt vmcnt(18)
	v_pk_add_f32 v[38:39], v[38:39], v[206:207]
	v_pk_add_f32 v[40:41], v[40:41], v[208:209]
	v_pk_add_f32 v[166:167], v[166:167], v[190:191] op_sel_hi:[1,0] neg_lo:[0,1] neg_hi:[0,1]
	v_pk_add_f32 v[168:169], v[168:169], v[190:191] op_sel_hi:[1,0] neg_lo:[0,1] neg_hi:[0,1]
	v_pk_mul_f32 v[166:167], v[166:167], v[190:191] op_sel:[0,1]
	v_pk_mul_f32 v[168:169], v[168:169], v[190:191] op_sel:[0,1]
	v_pk_fma_f32 v[166:167], v[198:199], v[166:167], v[202:203]
	v_pk_fma_f32 v[168:169], v[200:201], v[168:169], v[204:205]
	v_pk_fma_f32 v[166:167], v[38:39], v[194:195], v[166:167]
	v_pk_fma_f32 v[168:169], v[40:41], v[196:197], v[168:169]
	global_store_dwordx4 v230, v[166:169], s[8:9] offset:128
	s_nop 1
	global_load_dwordx4 v[166:169], v230, s[8:9] offset:192
	s_waitcnt vmcnt(18)
	v_pk_add_f32 v[34:35], v[34:35], v[206:207]
	v_pk_add_f32 v[36:37], v[36:37], v[208:209]
	v_pk_add_f32 v[170:171], v[170:171], v[192:193] op_sel_hi:[1,0] neg_lo:[0,1] neg_hi:[0,1]
	v_pk_add_f32 v[172:173], v[172:173], v[192:193] op_sel_hi:[1,0] neg_lo:[0,1] neg_hi:[0,1]
	v_pk_mul_f32 v[170:171], v[170:171], v[192:193] op_sel:[0,1]
	v_pk_mul_f32 v[172:173], v[172:173], v[192:193] op_sel:[0,1]
	v_pk_fma_f32 v[170:171], v[198:199], v[170:171], v[202:203]
	v_pk_fma_f32 v[172:173], v[200:201], v[172:173], v[204:205]
	v_pk_fma_f32 v[170:171], v[34:35], v[194:195], v[170:171]
	v_pk_fma_f32 v[172:173], v[36:37], v[196:197], v[172:173]
	global_store_dwordx4 v231, v[170:173], s[8:9] offset:128
	s_nop 1
	global_load_dwordx4 v[170:173], v231, s[8:9] offset:192
	s_waitcnt vmcnt(16)
	s_and_b64 vcc, exec, s[34:35]
	s_cbranch_vccnz .Ler_swa_hb3
	v_mov_b32_e32 v222, 0
	v_mov_b32_e32 v223, 0
	v_mov_b32_e32 v224, 0
	v_mov_b32_e32 v225, 0
.Ler_swa_hb3:
	v_pk_mul_f32 v[214:215], v[214:215], s[70:71] op_sel_hi:[1,0]
	v_pk_mul_f32 v[216:217], v[216:217], s[70:71] op_sel_hi:[1,0]
	v_pk_mul_f32 v[218:219], v[218:219], s[70:71] op_sel_hi:[1,0]
	v_pk_mul_f32 v[220:221], v[220:221], s[70:71] op_sel_hi:[1,0]
	s_waitcnt vmcnt(14)
	v_pk_add_f32 v[26:27], v[26:27], v[222:223]
	v_pk_add_f32 v[28:29], v[28:29], v[224:225]
	v_pk_add_f32 v[76:77], v[76:77], v[148:149] op_sel_hi:[1,0] neg_lo:[0,1] neg_hi:[0,1]
	v_pk_add_f32 v[78:79], v[78:79], v[148:149] op_sel_hi:[1,0] neg_lo:[0,1] neg_hi:[0,1]
	v_pk_mul_f32 v[76:77], v[76:77], v[148:149] op_sel:[0,1]
	v_pk_mul_f32 v[78:79], v[78:79], v[148:149] op_sel:[0,1]
	v_pk_fma_f32 v[76:77], v[214:215], v[76:77], v[218:219]
	v_pk_fma_f32 v[78:79], v[216:217], v[78:79], v[220:221]
	v_pk_fma_f32 v[76:77], v[26:27], v[210:211], v[76:77]
	v_pk_fma_f32 v[78:79], v[28:29], v[212:213], v[78:79]
	global_store_dwordx4 v63, v[76:79], s[8:9] offset:192
	s_waitcnt vmcnt(13)
	v_pk_add_f32 v[22:23], v[22:23], v[222:223]
	v_pk_add_f32 v[24:25], v[24:25], v[224:225]
	v_pk_add_f32 v[108:109], v[108:109], v[160:161] op_sel_hi:[1,0] neg_lo:[0,1] neg_hi:[0,1]
	v_pk_add_f32 v[110:111], v[110:111], v[160:161] op_sel_hi:[1,0] neg_lo:[0,1] neg_hi:[0,1]
	v_pk_mul_f32 v[108:109], v[108:109], v[160:161] op_sel:[0,1]
	v_pk_mul_f32 v[110:111], v[110:111], v[160:161] op_sel:[0,1]
	v_pk_fma_f32 v[108:109], v[214:215], v[108:109], v[218:219]
	v_pk_fma_f32 v[110:111], v[216:217], v[110:111], v[220:221]
	v_pk_fma_f32 v[108:109], v[22:23], v[210:211], v[108:109]
	v_pk_fma_f32 v[110:111], v[24:25], v[212:213], v[110:111]
	global_store_dwordx4 v151, v[108:111], s[8:9] offset:192
	s_waitcnt vmcnt(12)
	v_pk_add_f32 v[18:19], v[18:19], v[222:223]
	v_pk_add_f32 v[20:21], v[20:21], v[224:225]
	v_pk_add_f32 v[116:117], v[116:117], v[174:175] op_sel_hi:[1,0] neg_lo:[0,1] neg_hi:[0,1]
	v_pk_add_f32 v[118:119], v[118:119], v[174:175] op_sel_hi:[1,0] neg_lo:[0,1] neg_hi:[0,1]
	v_pk_mul_f32 v[116:117], v[116:117], v[174:175] op_sel:[0,1]
	v_pk_mul_f32 v[118:119], v[118:119], v[174:175] op_sel:[0,1]
	v_pk_fma_f32 v[116:117], v[214:215], v[116:117], v[218:219]
	v_pk_fma_f32 v[118:119], v[216:217], v[118:119], v[220:221]
	v_pk_fma_f32 v[116:117], v[18:19], v[210:211], v[116:117]
	v_pk_fma_f32 v[118:119], v[20:21], v[212:213], v[118:119]
	global_store_dwordx4 v226, v[116:119], s[8:9] offset:192
	s_waitcnt vmcnt(11)
	v_pk_add_f32 v[14:15], v[14:15], v[222:223]
	v_pk_add_f32 v[16:17], v[16:17], v[224:225]
	v_pk_add_f32 v[144:145], v[144:145], v[176:177] op_sel_hi:[1,0] neg_lo:[0,1] neg_hi:[0,1]
	v_pk_add_f32 v[146:147], v[146:147], v[176:177] op_sel_hi:[1,0] neg_lo:[0,1] neg_hi:[0,1]
	v_pk_mul_f32 v[144:145], v[144:145], v[176:177] op_sel:[0,1]
	v_pk_mul_f32 v[146:147], v[146:147], v[176:177] op_sel:[0,1]
	v_pk_fma_f32 v[144:145], v[214:215], v[144:145], v[218:219]
	v_pk_fma_f32 v[146:147], v[216:217], v[146:147], v[220:221]
	v_pk_fma_f32 v[144:145], v[14:15], v[210:211], v[144:145]
	v_pk_fma_f32 v[146:147], v[16:17], v[212:213], v[146:147]
	global_store_dwordx4 v227, v[144:147], s[8:9] offset:192
	s_waitcnt vmcnt(10)
	v_pk_add_f32 v[10:11], v[10:11], v[222:223]
	v_pk_add_f32 v[12:13], v[12:13], v[224:225]
	v_pk_add_f32 v[152:153], v[152:153], v[186:187] op_sel_hi:[1,0] neg_lo:[0,1] neg_hi:[0,1]
	v_pk_add_f32 v[154:155], v[154:155], v[186:187] op_sel_hi:[1,0] neg_lo:[0,1] neg_hi:[0,1]
	v_pk_mul_f32 v[152:153], v[152:153], v[186:187] op_sel:[0,1]
	v_pk_mul_f32 v[154:155], v[154:155], v[186:187] op_sel:[0,1]
	v_pk_fma_f32 v[152:153], v[214:215], v[152:153], v[218:219]
	v_pk_fma_f32 v[154:155], v[216:217], v[154:155], v[220:221]
	v_pk_fma_f32 v[152:153], v[10:11], v[210:211], v[152:153]
	v_pk_fma_f32 v[154:155], v[12:13], v[212:213], v[154:155]
	global_store_dwordx4 v228, v[152:155], s[8:9] offset:192
	s_waitcnt vmcnt(9)
	v_pk_add_f32 v[6:7], v[6:7], v[222:223]
	v_pk_add_f32 v[8:9], v[8:9], v[224:225]
	v_pk_add_f32 v[156:157], v[156:157], v[188:189] op_sel_hi:[1,0] neg_lo:[0,1] neg_hi:[0,1]
	v_pk_add_f32 v[158:159], v[158:159], v[188:189] op_sel_hi:[1,0] neg_lo:[0,1] neg_hi:[0,1]
	v_pk_mul_f32 v[156:157], v[156:157], v[188:189] op_sel:[0,1]
	v_pk_mul_f32 v[158:159], v[158:159], v[188:189] op_sel:[0,1]
	v_pk_fma_f32 v[156:157], v[214:215], v[156:157], v[218:219]
	v_pk_fma_f32 v[158:159], v[216:217], v[158:159], v[220:221]
	v_pk_fma_f32 v[156:157], v[6:7], v[210:211], v[156:157]
	v_pk_fma_f32 v[158:159], v[8:9], v[212:213], v[158:159]
	global_store_dwordx4 v229, v[156:159], s[8:9] offset:192
	s_waitcnt vmcnt(8)
	v_pk_add_f32 v[2:3], v[2:3], v[222:223]
	v_pk_add_f32 v[4:5], v[4:5], v[224:225]
	v_pk_add_f32 v[166:167], v[166:167], v[190:191] op_sel_hi:[1,0] neg_lo:[0,1] neg_hi:[0,1]
	v_pk_add_f32 v[168:169], v[168:169], v[190:191] op_sel_hi:[1,0] neg_lo:[0,1] neg_hi:[0,1]
	v_pk_mul_f32 v[166:167], v[166:167], v[190:191] op_sel:[0,1]
	v_pk_mul_f32 v[168:169], v[168:169], v[190:191] op_sel:[0,1]
	v_pk_fma_f32 v[166:167], v[214:215], v[166:167], v[218:219]
	v_pk_fma_f32 v[168:169], v[216:217], v[168:169], v[220:221]
	v_pk_fma_f32 v[166:167], v[2:3], v[210:211], v[166:167]
	v_pk_fma_f32 v[168:169], v[4:5], v[212:213], v[168:169]
	global_store_dwordx4 v230, v[166:169], s[8:9] offset:192
	s_waitcnt vmcnt(7)
	v_pk_add_f32 v[30:31], v[30:31], v[222:223]
	v_pk_add_f32 v[32:33], v[32:33], v[224:225]
	v_pk_add_f32 v[170:171], v[170:171], v[192:193] op_sel_hi:[1,0] neg_lo:[0,1] neg_hi:[0,1]
	v_pk_add_f32 v[172:173], v[172:173], v[192:193] op_sel_hi:[1,0] neg_lo:[0,1] neg_hi:[0,1]
	v_pk_mul_f32 v[170:171], v[170:171], v[192:193] op_sel:[0,1]
	v_pk_mul_f32 v[172:173], v[172:173], v[192:193] op_sel:[0,1]
	v_pk_fma_f32 v[170:171], v[214:215], v[170:171], v[218:219]
	v_pk_fma_f32 v[172:173], v[216:217], v[172:173], v[220:221]
	v_pk_fma_f32 v[170:171], v[30:31], v[210:211], v[170:171]
	v_pk_fma_f32 v[172:173], v[32:33], v[212:213], v[172:173]
	global_store_dwordx4 v231, v[170:173], s[8:9] offset:192
	s_add_i32 s61, s61, s30
	s_cmpk_gt_i32 s61, 0xff
	s_cbranch_scc1 .LBB0_470
	s_branch .LBB0_456
